# grid barrier: L1 invalidate issued by wave 1 right after the workgroup parks (not in wave 0's vmcnt queue)
# speedup vs baseline: 1.0008x; 1.0008x over previous
.LBB0_42:
	s_waitcnt vmcnt(0)
	s_waitcnt lgkmcnt(0)
	s_barrier
	s_mov_b64 s[0:1], exec
	v_readfirstlane_b32 s101, v224
	s_lshr_b32 s101, s101, 6
	s_cmp_lg_u32 s101, 1
	s_cbranch_scc1 .Lbinv_skip0
	buffer_inv sc1
	s_waitcnt vmcnt(0)
.Lbinv_skip0:
	v_readlane_b32 s4, v254, 9
	s_mov_b32 s6, s72
	v_readlane_b32 s5, v254, 10
	v_writelane_b32 v254, s6, 13
	s_and_b64 s[4:5], s[0:1], s[4:5]
	s_nop 0
	v_writelane_b32 v254, s7, 14
	v_writelane_b32 v254, s90, 15
	s_nop 1
	v_writelane_b32 v254, s91, 16
	v_writelane_b32 v254, s78, 17
	s_mov_b64 exec, s[4:5]
	s_cbranch_execz .LBB0_94
	s_add_i32 s3, 0, 0x20000
	v_mov_b32_e32 v0, s3
	s_waitcnt vmcnt(0) expcnt(0) lgkmcnt(0)
	ds_read_b32 v2, v0
	s_add_i32 s3, 0, 0x20004
	v_mov_b32_e32 v0, s3
	ds_read_b32 v0, v0
	s_waitcnt lgkmcnt(1)
	v_cmp_ne_u32_e32 vcc, 0, v2
	s_cbranch_vccnz .LBB0_58
	s_add_u32 s4, s24, 0xed22200
	s_addc_u32 s5, s25, 0
	s_add_u32 s6, s24, 0xed22400
	s_addc_u32 s7, s25, 0
	s_add_u32 s8, s24, 0xed22500
	s_addc_u32 s9, s25, 0
	s_add_u32 s10, s24, 0xed22600
	s_addc_u32 s11, s25, 0
	s_add_u32 s12, s24, 0xed22700
	s_addc_u32 s13, s25, 0
	s_add_u32 s14, s24, 0xed22800
	s_addc_u32 s15, s25, 0
	s_add_u32 s30, s24, 0xed22900
	s_addc_u32 s31, s25, 0
	s_add_u32 s34, s24, 0xed22a00
	s_addc_u32 s35, s25, 0
	s_add_u32 s56, s24, 0xed22b00
	s_addc_u32 s57, s25, 0
	s_add_u32 s80, s24, 0xed22c00
	s_addc_u32 s81, s25, 0
	s_add_u32 s82, s24, 0xed22d00
	s_addc_u32 s83, s25, 0
	s_add_u32 s84, s24, 0xed22e00
	s_addc_u32 s85, s25, 0
	s_add_u32 s86, s24, 0xed22f00
	s_addc_u32 s87, s25, 0
	s_add_u32 s88, s24, 0xed23000
	s_addc_u32 s89, s25, 0
	s_add_u32 s90, s24, 0xed23100
	s_addc_u32 s91, s25, 0
	s_add_u32 s92, s24, 0xed23200
	v_readlane_b32 s3, v254, 8
	s_addc_u32 s93, s25, 0
	s_mul_i32 s3, s27, s3
	s_add_u32 s94, s24, 0xed23300
	s_mul_i32 s3, s3, s26
	s_addc_u32 s95, s25, 0
	s_mov_b32 s19, 1
	v_mov_b32_e32 v16, 0
	s_branch .LBB0_46

.LBB0_170:
	s_or_b64 exec, exec, s[0:1]
	s_waitcnt vmcnt(0)
	s_barrier
	s_mov_b64 s[0:1], exec
	v_readfirstlane_b32 s101, v224
	s_lshr_b32 s101, s101, 6
	s_cmp_lg_u32 s101, 1
	s_cbranch_scc1 .Lbinv_skip1
	buffer_inv sc1
	s_waitcnt vmcnt(0)
.Lbinv_skip1:
	v_readlane_b32 s4, v254, 9
	v_readlane_b32 s5, v254, 10
	s_and_b64 s[4:5], s[0:1], s[4:5]
	s_xor_b64 s[0:1], s[4:5], s[0:1]
	s_mov_b64 exec, s[4:5]
	s_cbranch_execz .LBB0_223
	s_add_i32 s3, 0, 0x20000
	v_mov_b32_e32 v0, s3
	s_waitcnt vmcnt(0) expcnt(0) lgkmcnt(0)
	ds_read_b32 v2, v0
	s_add_i32 s3, 0, 0x20004
	v_mov_b32_e32 v0, s3
	ds_read_b32 v0, v0
	s_waitcnt lgkmcnt(1)
	v_cmp_ne_u32_e32 vcc, 0, v2
	s_cbranch_vccnz .LBB0_186
	s_add_u32 s4, s24, 0xed22200
	s_addc_u32 s5, s25, 0
	s_add_u32 s6, s24, 0xed22400
	s_addc_u32 s7, s25, 0
	s_add_u32 s8, s24, 0xed22500
	s_addc_u32 s9, s25, 0
	s_add_u32 s10, s24, 0xed22600
	s_addc_u32 s11, s25, 0
	s_add_u32 s12, s24, 0xed22700
	s_addc_u32 s13, s25, 0
	s_add_u32 s14, s24, 0xed22800
	s_addc_u32 s15, s25, 0
	s_add_u32 s34, s24, 0xed22900
	s_addc_u32 s35, s25, 0
	s_add_u32 s56, s24, 0xed22a00
	s_addc_u32 s57, s25, 0
	s_add_u32 s80, s24, 0xed22b00
	s_addc_u32 s81, s25, 0
	s_add_u32 s82, s24, 0xed22c00
	s_addc_u32 s83, s25, 0
	s_add_u32 s84, s24, 0xed22d00
	s_addc_u32 s85, s25, 0
	s_add_u32 s86, s24, 0xed22e00
	s_addc_u32 s87, s25, 0
	s_add_u32 s88, s24, 0xed22f00
	s_addc_u32 s89, s25, 0
	s_add_u32 s90, s24, 0xed23000
	s_addc_u32 s91, s25, 0
	s_add_u32 s92, s24, 0xed23100
	s_addc_u32 s93, s25, 0
	s_add_u32 s94, s24, 0xed23200
	v_readlane_b32 s3, v254, 8
	s_addc_u32 s95, s25, 0
	s_mul_i32 s3, s27, s3
	s_add_u32 s96, s24, 0xed23300
	s_mul_i32 s3, s3, s26
	s_addc_u32 s97, s25, 0
	s_mov_b32 s19, 1
	v_mov_b32_e32 v16, 0
	s_branch .LBB0_174

.LBB0_761:
	s_waitcnt vmcnt(0)
	s_waitcnt vmcnt(0) lgkmcnt(0)
	s_barrier
	s_mov_b64 s[0:1], exec
	v_readfirstlane_b32 s101, v224
	s_lshr_b32 s101, s101, 6
	s_cmp_lg_u32 s101, 1
	s_cbranch_scc1 .Lbinv_skip2
	buffer_inv sc1
	s_waitcnt vmcnt(0)
.Lbinv_skip2:
	v_readlane_b32 s4, v254, 9
	v_readlane_b32 s5, v254, 10
	s_and_b64 s[4:5], s[0:1], s[4:5]
	s_xor_b64 s[0:1], s[4:5], s[0:1]
	s_mov_b64 exec, s[4:5]
	s_cbranch_execz .LBB0_814
	s_add_i32 s3, 0, 0x20000
	v_mov_b32_e32 v0, s3
	s_waitcnt vmcnt(0) expcnt(0) lgkmcnt(0)
	ds_read_b32 v2, v0
	s_add_i32 s3, 0, 0x20004
	v_mov_b32_e32 v0, s3
	ds_read_b32 v0, v0
	s_waitcnt lgkmcnt(1)
	v_cmp_ne_u32_e32 vcc, 0, v2
	s_cbranch_vccnz .LBB0_777
	s_add_u32 s4, s24, 0xed22200
	s_addc_u32 s5, s25, 0
	s_add_u32 s6, s24, 0xed22400
	s_addc_u32 s7, s25, 0
	s_add_u32 s8, s24, 0xed22500
	s_addc_u32 s9, s25, 0
	s_add_u32 s10, s24, 0xed22600
	s_addc_u32 s11, s25, 0
	s_add_u32 s12, s24, 0xed22700
	s_addc_u32 s13, s25, 0
	s_add_u32 s14, s24, 0xed22800
	s_addc_u32 s15, s25, 0
	s_add_u32 s56, s24, 0xed22900
	s_addc_u32 s57, s25, 0
	s_add_u32 s58, s24, 0xed22a00
	s_addc_u32 s59, s25, 0
	s_add_u32 s62, s24, 0xed22b00
	s_addc_u32 s63, s25, 0
	s_add_u32 s80, s24, 0xed22c00
	s_addc_u32 s81, s25, 0
	s_add_u32 s82, s24, 0xed22d00
	s_addc_u32 s83, s25, 0
	s_add_u32 s86, s24, 0xed22e00
	s_addc_u32 s87, s25, 0
	s_add_u32 s88, s24, 0xed22f00
	s_addc_u32 s89, s25, 0
	s_add_u32 s90, s24, 0xed23000
	s_addc_u32 s91, s25, 0
	s_add_u32 s92, s24, 0xed23100
	s_addc_u32 s93, s25, 0
	s_add_u32 s94, s24, 0xed23200
	v_readlane_b32 s3, v254, 8
	s_addc_u32 s95, s25, 0
	s_mul_i32 s3, s27, s3
	s_add_u32 s96, s24, 0xed23300
	s_mul_i32 s3, s3, s26
	s_addc_u32 s97, s25, 0
	s_mov_b32 s19, 1
	v_mov_b32_e32 v16, 0
	s_branch .LBB0_765

.LBB0_935:
	s_waitcnt vmcnt(0)
	s_barrier
	s_mov_b64 s[0:1], exec
	v_readfirstlane_b32 s101, v224
	s_lshr_b32 s101, s101, 6
	s_cmp_lg_u32 s101, 1
	s_cbranch_scc1 .Lbinv_skip3
	buffer_inv sc1
	s_waitcnt vmcnt(0)
.Lbinv_skip3:
	v_readlane_b32 s4, v254, 9
	v_readlane_b32 s5, v254, 10
	s_and_b64 s[4:5], s[0:1], s[4:5]
	s_xor_b64 s[0:1], s[4:5], s[0:1]
	s_mov_b64 exec, s[4:5]
	s_cbranch_execz .LBB0_989
	s_add_i32 s3, 0, 0x20000
	v_mov_b32_e32 v0, s3
	s_waitcnt vmcnt(0) expcnt(0) lgkmcnt(0)
	ds_read_b32 v2, v0
	s_add_i32 s3, 0, 0x20004
	v_mov_b32_e32 v0, s3
	ds_read_b32 v0, v0
	s_waitcnt lgkmcnt(1)
	v_cmp_ne_u32_e32 vcc, 0, v2
	s_cbranch_vccnz .LBB0_952
	s_add_u32 s4, s24, 0xed22200
	s_addc_u32 s5, s25, 0
	s_add_u32 s10, s24, 0xed22400
	s_addc_u32 s11, s25, 0
	s_add_u32 s12, s24, 0xed22500
	s_addc_u32 s13, s25, 0
	s_add_u32 s40, s24, 0xed22600
	s_addc_u32 s41, s25, 0
	s_add_u32 s42, s24, 0xed22700
	s_addc_u32 s43, s25, 0
	s_add_u32 s46, s24, 0xed22800
	s_addc_u32 s47, s25, 0
	s_add_u32 s48, s24, 0xed22900
	s_addc_u32 s49, s25, 0
	s_add_u32 s52, s24, 0xed22a00
	s_addc_u32 s53, s25, 0
	s_add_u32 s56, s24, 0xed22b00
	s_addc_u32 s57, s25, 0
	s_add_u32 s62, s24, 0xed22c00
	s_addc_u32 s63, s25, 0
	s_add_u32 s66, s24, 0xed22d00
	s_addc_u32 s67, s25, 0
	s_add_u32 s68, s24, 0xed22e00
	s_addc_u32 s69, s25, 0
	s_add_u32 s74, s24, 0xed22f00
	s_addc_u32 s75, s25, 0
	s_add_u32 s80, s24, 0xed23000
	s_addc_u32 s81, s25, 0
	s_add_u32 s82, s24, 0xed23100
	s_addc_u32 s83, s25, 0
	s_add_u32 s84, s24, 0xed23200
	v_readlane_b32 s3, v254, 8
	s_addc_u32 s85, s25, 0
	s_mul_i32 s3, s27, s3
	s_add_u32 s86, s24, 0xed23300
	s_mul_i32 s3, s3, s26
	s_addc_u32 s87, s25, 0
	s_mov_b32 s19, 1
	v_mov_b32_e32 v16, 0
	s_branch .LBB0_940

.Lbinv_skip4:
	v_readlane_b32 s4, v254, 9
	v_readlane_b32 s5, v254, 10
	s_and_b64 s[4:5], s[0:1], s[4:5]
	s_xor_b64 s[0:1], s[4:5], s[0:1]
	s_mov_b64 exec, s[4:5]
	s_cbranch_execz .LBB0_1059
	s_add_i32 s3, 0, 0x20000
	v_mov_b32_e32 v0, s3
	s_waitcnt vmcnt(0) expcnt(0) lgkmcnt(0)
	ds_read_b32 v2, v0
	s_add_i32 s3, 0, 0x20004
	v_mov_b32_e32 v0, s3
	ds_read_b32 v0, v0
	s_waitcnt lgkmcnt(1)
	v_cmp_ne_u32_e32 vcc, 0, v2
	s_cbranch_vccnz .LBB0_1022
	s_add_u32 s4, s24, 0xed22200
	s_addc_u32 s5, s25, 0
	s_add_u32 s10, s24, 0xed22400
	s_addc_u32 s11, s25, 0
	s_add_u32 s12, s24, 0xed22500
	s_addc_u32 s13, s25, 0
	s_add_u32 s40, s24, 0xed22600
	s_addc_u32 s41, s25, 0
	s_add_u32 s42, s24, 0xed22700
	s_addc_u32 s43, s25, 0
	s_add_u32 s46, s24, 0xed22800
	s_addc_u32 s47, s25, 0
	s_add_u32 s48, s24, 0xed22900
	s_addc_u32 s49, s25, 0
	s_add_u32 s52, s24, 0xed22a00
	s_addc_u32 s53, s25, 0
	s_add_u32 s56, s24, 0xed22b00
	s_addc_u32 s57, s25, 0
	s_add_u32 s62, s24, 0xed22c00
	s_addc_u32 s63, s25, 0
	s_add_u32 s64, s24, 0xed22d00
	s_addc_u32 s65, s25, 0
	s_add_u32 s66, s24, 0xed22e00
	s_addc_u32 s67, s25, 0
	s_add_u32 s68, s24, 0xed22f00
	s_addc_u32 s69, s25, 0
	s_add_u32 s74, s24, 0xed23000
	s_addc_u32 s75, s25, 0
	s_add_u32 s80, s24, 0xed23100
	s_addc_u32 s81, s25, 0
	s_add_u32 s82, s24, 0xed23200
	v_readlane_b32 s3, v254, 8
	s_addc_u32 s83, s25, 0
	s_mul_i32 s3, s27, s3
	s_add_u32 s84, s24, 0xed23300
	s_mul_i32 s3, s3, s26
	s_addc_u32 s85, s25, 0
	s_mov_b32 s19, 1
	v_mov_b32_e32 v16, 0
	s_branch .LBB0_1010

.Lbinv_skip5:
	v_readlane_b32 s4, v254, 9
	v_readlane_b32 s5, v254, 10
	s_and_b64 s[4:5], s[0:1], s[4:5]
	s_xor_b64 s[0:1], s[4:5], s[0:1]
	s_mov_b64 exec, s[4:5]
	s_cbranch_execz .LBB0_1125
	s_add_i32 s3, 0, 0x20000
	v_mov_b32_e32 v0, s3
	s_waitcnt vmcnt(0) expcnt(0) lgkmcnt(0)
	ds_read_b32 v2, v0
	s_add_i32 s3, 0, 0x20004
	v_mov_b32_e32 v0, s3
	ds_read_b32 v0, v0
	s_waitcnt lgkmcnt(1)
	v_cmp_ne_u32_e32 vcc, 0, v2
	s_cbranch_vccnz .LBB0_1088
	s_add_u32 s4, s24, 0xed22200
	s_addc_u32 s5, s25, 0
	s_add_u32 s6, s24, 0xed22400
	s_addc_u32 s7, s25, 0
	s_add_u32 s40, s24, 0xed22500
	s_addc_u32 s41, s25, 0
	s_add_u32 s42, s24, 0xed22600
	s_addc_u32 s43, s25, 0
	s_add_u32 s46, s24, 0xed22700
	s_addc_u32 s47, s25, 0
	s_add_u32 s48, s24, 0xed22800
	s_addc_u32 s49, s25, 0
	s_add_u32 s52, s24, 0xed22900
	s_addc_u32 s53, s25, 0
	s_add_u32 s56, s24, 0xed22a00
	s_addc_u32 s57, s25, 0
	s_add_u32 s62, s24, 0xed22b00
	s_addc_u32 s63, s25, 0
	s_add_u32 s64, s24, 0xed22c00
	s_addc_u32 s65, s25, 0
	s_add_u32 s66, s24, 0xed22d00
	s_addc_u32 s67, s25, 0
	s_add_u32 s68, s24, 0xed22e00
	s_addc_u32 s69, s25, 0
	s_add_u32 s74, s24, 0xed22f00
	s_addc_u32 s75, s25, 0
	s_add_u32 s80, s24, 0xed23000
	s_addc_u32 s81, s25, 0
	s_add_u32 s82, s24, 0xed23100
	s_addc_u32 s83, s25, 0
	s_add_u32 s84, s24, 0xed23200
	v_readlane_b32 s3, v254, 8
	s_addc_u32 s85, s25, 0
	s_mul_i32 s3, s27, s3
	s_add_u32 s86, s24, 0xed23300
	s_mul_i32 s3, s3, s26
	s_addc_u32 s87, s25, 0
	s_mov_b32 s19, 1
	v_mov_b32_e32 v16, 0
	s_branch .LBB0_1076

.Lbinv_skip6:
	v_readlane_b32 s4, v254, 9
	v_readlane_b32 s5, v254, 10
	s_and_b64 s[4:5], s[0:1], s[4:5]
	s_mov_b64 exec, s[4:5]
	s_cbranch_execz .LBB0_1254
	s_add_i32 s3, 0, 0x20000
	v_mov_b32_e32 v0, s3
	s_waitcnt vmcnt(0) expcnt(0) lgkmcnt(0)
	ds_read_b32 v2, v0
	s_add_i32 s3, 0, 0x20004
	v_mov_b32_e32 v0, s3
	ds_read_b32 v0, v0
	s_waitcnt lgkmcnt(1)
	v_cmp_ne_u32_e32 vcc, 0, v2
	s_cbranch_vccnz .LBB0_1218
	s_add_u32 s4, s24, 0xed22200
	s_addc_u32 s5, s25, 0
	s_add_u32 s6, s24, 0xed22400
	s_addc_u32 s7, s25, 0
	s_add_u32 s36, s24, 0xed22500
	s_addc_u32 s37, s25, 0
	s_add_u32 s38, s24, 0xed22600
	s_addc_u32 s39, s25, 0
	s_add_u32 s40, s24, 0xed22700
	s_addc_u32 s41, s25, 0
	s_add_u32 s42, s24, 0xed22800
	s_addc_u32 s43, s25, 0
	s_add_u32 s46, s24, 0xed22900
	s_addc_u32 s47, s25, 0
	s_add_u32 s48, s24, 0xed22a00
	s_addc_u32 s49, s25, 0
	s_add_u32 s50, s24, 0xed22b00
	s_addc_u32 s51, s25, 0
	s_add_u32 s52, s24, 0xed22c00
	s_addc_u32 s53, s25, 0
	s_add_u32 s54, s24, 0xed22d00
	s_addc_u32 s55, s25, 0
	s_add_u32 s56, s24, 0xed22e00
	s_addc_u32 s57, s25, 0
	s_add_u32 s62, s24, 0xed22f00
	s_addc_u32 s63, s25, 0
	s_add_u32 s64, s24, 0xed23000
	s_addc_u32 s65, s25, 0
	s_add_u32 s66, s24, 0xed23100
	s_addc_u32 s67, s25, 0
	s_add_u32 s68, s24, 0xed23200
	v_readlane_b32 s3, v254, 8
	s_addc_u32 s69, s25, 0
	s_mul_i32 s3, s27, s3
	s_add_u32 s74, s24, 0xed23300
	s_mul_i32 s3, s3, s26
	s_addc_u32 s75, s25, 0
	s_mov_b32 s19, 1
	v_mov_b32_e32 v16, 0
	s_branch .LBB0_1206

.Lbinv_skip7:
	v_readlane_b32 s4, v254, 9
	v_readlane_b32 s5, v254, 10
	s_and_b64 s[4:5], s[0:1], s[4:5]
	s_xor_b64 s[0:1], s[4:5], s[0:1]
	s_mov_b64 exec, s[4:5]
	s_cbranch_execz .LBB0_1353
	s_add_i32 s3, 0, 0x20000
	v_mov_b32_e32 v0, s3
	s_waitcnt vmcnt(0) expcnt(0) lgkmcnt(0)
	ds_read_b32 v2, v0
	s_add_i32 s3, 0, 0x20004
	v_mov_b32_e32 v0, s3
	ds_read_b32 v0, v0
	s_waitcnt lgkmcnt(1)
	v_cmp_ne_u32_e32 vcc, 0, v2
	s_cbranch_vccnz .LBB0_1316
	s_add_u32 s4, s24, 0xed22200
	s_addc_u32 s5, s25, 0
	s_add_u32 s6, s24, 0xed22400
	s_addc_u32 s7, s25, 0
	s_add_u32 s14, s24, 0xed22500
	s_addc_u32 s15, s25, 0
	s_add_u32 s36, s24, 0xed22600
	s_addc_u32 s37, s25, 0
	s_add_u32 s38, s24, 0xed22700
	s_addc_u32 s39, s25, 0
	s_add_u32 s40, s24, 0xed22800
	s_addc_u32 s41, s25, 0
	s_add_u32 s42, s24, 0xed22900
	s_addc_u32 s43, s25, 0
	s_add_u32 s46, s24, 0xed22a00
	s_addc_u32 s47, s25, 0
	s_add_u32 s48, s24, 0xed22b00
	s_addc_u32 s49, s25, 0
	s_add_u32 s50, s24, 0xed22c00
	s_addc_u32 s51, s25, 0
	s_add_u32 s52, s24, 0xed22d00
	s_addc_u32 s53, s25, 0
	s_add_u32 s54, s24, 0xed22e00
	s_addc_u32 s55, s25, 0
	s_add_u32 s56, s24, 0xed22f00
	s_addc_u32 s57, s25, 0
	s_add_u32 s62, s24, 0xed23000
	s_addc_u32 s63, s25, 0
	s_add_u32 s64, s24, 0xed23100
	s_addc_u32 s65, s25, 0
	s_add_u32 s66, s24, 0xed23200
	v_readlane_b32 s3, v254, 8
	s_addc_u32 s67, s25, 0
	s_mul_i32 s3, s27, s3
	s_add_u32 s68, s24, 0xed23300
	s_mul_i32 s3, s3, s26
	s_addc_u32 s69, s25, 0
	s_mov_b32 s19, 1
	v_mov_b32_e32 v16, 0
	s_branch .LBB0_1304

.Lbinv_skip8:
	v_readlane_b32 s4, v254, 9
	v_readlane_b32 s5, v254, 10
	s_and_b64 s[4:5], s[0:1], s[4:5]
	s_xor_b64 s[0:1], s[4:5], s[0:1]
	s_mov_b64 exec, s[4:5]
	s_cbranch_execz .LBB0_1426
	s_add_i32 s3, 0, 0x20000
	v_mov_b32_e32 v0, s3
	s_waitcnt vmcnt(0) expcnt(0) lgkmcnt(0)
	ds_read_b32 v2, v0
	s_add_i32 s3, 0, 0x20004
	v_mov_b32_e32 v0, s3
	ds_read_b32 v0, v0
	s_waitcnt lgkmcnt(1)
	v_cmp_ne_u32_e32 vcc, 0, v2
	s_cbranch_vccnz .LBB0_1389
	s_add_u32 s4, s24, 0xed22200
	s_addc_u32 s5, s25, 0
	s_add_u32 s6, s24, 0xed22400
	s_addc_u32 s7, s25, 0
	s_add_u32 s14, s24, 0xed22500
	s_addc_u32 s15, s25, 0
	s_add_u32 s36, s24, 0xed22600
	s_addc_u32 s37, s25, 0
	s_add_u32 s38, s24, 0xed22700
	s_addc_u32 s39, s25, 0
	s_add_u32 s40, s24, 0xed22800
	s_addc_u32 s41, s25, 0
	s_add_u32 s42, s24, 0xed22900
	s_addc_u32 s43, s25, 0
	s_add_u32 s44, s24, 0xed22a00
	s_addc_u32 s45, s25, 0
	s_add_u32 s46, s24, 0xed22b00
	s_addc_u32 s47, s25, 0
	s_add_u32 s48, s24, 0xed22c00
	s_addc_u32 s49, s25, 0
	s_add_u32 s50, s24, 0xed22d00
	s_addc_u32 s51, s25, 0
	s_add_u32 s52, s24, 0xed22e00
	s_addc_u32 s53, s25, 0
	s_add_u32 s54, s24, 0xed22f00
	s_addc_u32 s55, s25, 0
	s_add_u32 s56, s24, 0xed23000
	s_addc_u32 s57, s25, 0
	s_add_u32 s58, s24, 0xed23100
	s_addc_u32 s59, s25, 0
	s_add_u32 s62, s24, 0xed23200
	v_readlane_b32 s3, v254, 8
	s_addc_u32 s63, s25, 0
	s_mul_i32 s3, s27, s3
	s_add_u32 s64, s24, 0xed23300
	s_mul_i32 s3, s3, s26
	s_addc_u32 s65, s25, 0
	s_mov_b32 s19, 1
	v_mov_b32_e32 v16, 0
	s_branch .LBB0_1377

.Lbinv_skip9:
	v_readlane_b32 s4, v254, 9
	v_readlane_b32 s5, v254, 10
	s_and_b64 s[4:5], s[0:1], s[4:5]
	s_xor_b64 s[0:1], s[4:5], s[0:1]
	s_mov_b64 exec, s[4:5]
	s_cbranch_execz .LBB0_1492
	s_add_i32 s3, 0, 0x20000
	v_mov_b32_e32 v0, s3
	s_waitcnt vmcnt(0) expcnt(0) lgkmcnt(0)
	ds_read_b32 v2, v0
	s_add_i32 s3, 0, 0x20004
	v_mov_b32_e32 v0, s3
	ds_read_b32 v0, v0
	s_waitcnt lgkmcnt(1)
	v_cmp_ne_u32_e32 vcc, 0, v2
	s_cbranch_vccnz .LBB0_1455
	s_add_u32 s4, s24, 0xed22200
	s_addc_u32 s5, s25, 0
	s_add_u32 s6, s24, 0xed22400
	s_addc_u32 s7, s25, 0
	s_add_u32 s14, s24, 0xed22500
	s_addc_u32 s15, s25, 0
	s_add_u32 s36, s24, 0xed22600
	s_addc_u32 s37, s25, 0
	s_add_u32 s38, s24, 0xed22700
	s_addc_u32 s39, s25, 0
	s_add_u32 s40, s24, 0xed22800
	s_addc_u32 s41, s25, 0
	s_add_u32 s42, s24, 0xed22900
	s_addc_u32 s43, s25, 0
	s_add_u32 s44, s24, 0xed22a00
	s_addc_u32 s45, s25, 0
	s_add_u32 s46, s24, 0xed22b00
	s_addc_u32 s47, s25, 0
	s_add_u32 s48, s24, 0xed22c00
	s_addc_u32 s49, s25, 0
	s_add_u32 s50, s24, 0xed22d00
	s_addc_u32 s51, s25, 0
	s_add_u32 s52, s24, 0xed22e00
	s_addc_u32 s53, s25, 0
	s_add_u32 s54, s24, 0xed22f00
	s_addc_u32 s55, s25, 0
	s_add_u32 s56, s24, 0xed23000
	s_addc_u32 s57, s25, 0
	s_add_u32 s58, s24, 0xed23100
	s_addc_u32 s59, s25, 0
	s_add_u32 s60, s24, 0xed23200
	v_readlane_b32 s3, v254, 8
	s_addc_u32 s61, s25, 0
	s_mul_i32 s3, s27, s3
	s_add_u32 s62, s24, 0xed23300
	s_mul_i32 s3, s3, s26
	s_addc_u32 s63, s25, 0
	s_mov_b32 s19, 1
	v_mov_b32_e32 v16, 0
	s_branch .LBB0_1443

.Lbinv_skip10:
	v_readlane_b32 s2, v254, 9
	v_readlane_b32 s3, v254, 10
	s_and_b64 s[2:3], s[0:1], s[2:3]
	s_mov_b64 exec, s[2:3]
	s_cbranch_execz .LBB0_1556
	s_add_i32 s2, 0, 0x20000
	v_mov_b32_e32 v0, s2
	s_waitcnt vmcnt(0) expcnt(0) lgkmcnt(0)
	ds_read_b32 v2, v0
	s_add_i32 s2, 0, 0x20004
	v_mov_b32_e32 v0, s2
	ds_read_b32 v0, v0
	s_waitcnt lgkmcnt(1)
	v_cmp_ne_u32_e32 vcc, 0, v2
	s_cbranch_vccnz .LBB0_1520
	v_readlane_b32 s2, v254, 8
	s_mul_i32 s19, s27, s2
	s_add_u32 s2, s24, 0xed22200
	s_addc_u32 s3, s25, 0
	s_add_u32 s6, s24, 0xed22400
	s_addc_u32 s7, s25, 0
	s_add_u32 s8, s24, 0xed22500
	s_addc_u32 s9, s25, 0
	s_add_u32 s12, s24, 0xed22600
	s_addc_u32 s13, s25, 0
	s_add_u32 s14, s24, 0xed22700
	s_addc_u32 s15, s25, 0
	s_add_u32 s16, s24, 0xed22800
	s_addc_u32 s17, s25, 0
	s_add_u32 s30, s24, 0xed22900
	s_addc_u32 s31, s25, 0
	s_add_u32 s36, s24, 0xed22a00
	s_addc_u32 s37, s25, 0
	s_add_u32 s38, s24, 0xed22b00
	s_addc_u32 s39, s25, 0
	s_add_u32 s40, s24, 0xed22c00
	s_addc_u32 s41, s25, 0
	s_add_u32 s42, s24, 0xed22d00
	s_addc_u32 s43, s25, 0
	s_add_u32 s44, s24, 0xed22e00
	s_addc_u32 s45, s25, 0
	s_add_u32 s46, s24, 0xed22f00
	s_addc_u32 s47, s25, 0
	s_add_u32 s48, s24, 0xed23000
	s_addc_u32 s49, s25, 0
	s_add_u32 s50, s24, 0xed23100
	s_addc_u32 s51, s25, 0
	s_add_u32 s52, s24, 0xed23200
	s_addc_u32 s53, s25, 0
	s_add_u32 s54, s24, 0xed23300
	s_mul_i32 s19, s19, s26
	s_addc_u32 s55, s25, 0
	s_mov_b32 s27, 1
	v_mov_b32_e32 v16, 0
	s_branch .LBB0_1508
